# diff-attention softmax row sum split into two interleaved scalar add chains (was one 32-long serial chain), on top of attention setprio
# baseline (speedup 1.0000x reference)
; __device__ __forceinline__ void finishSM(f32x16& p0, f32x16& p1, float alpha, float& l_reg, bf16x8& pa0, bf16x8& pa1, bf16x8& pa2, bf16x8& pa3) {
; #pragma unroll
;   for (int r = 0; r < 16; ++r) p1[r] = __builtin_amdgcn_exp2f(p1[r]);
;   float ps = 0;
; #pragma unroll
;   for (int r = 0; r < 16; ++r) ps += p0[r];
; #pragma unroll
;   for (int r = 0; r < 16; ++r) ps += p1[r];
;   { auto rr = __builtin_amdgcn_permlane32_swap(__float_as_uint(ps), __float_as_uint(ps), false, false);
;     ps = __uint_as_float(rr[0]) + __uint_as_float(rr[1]); }
;   l_reg = l_reg * alpha + ps;
;     ...
;   PK4(p0, 0, pa0); PK4(p0, 8, pa1); PK4(p1, 0, pa2); PK4(p1, 8, pa3);
;     ...
; }
; template <int NQ> __device__ __forceinline__ void qkt(f32x16& p0, f32x16& p1, const char* Ks, const bf16x8* qr, int r32, int hi, int kcolB) {
;   p0 = f32x16{}; p1 = f32x16{};
; #pragma unroll
;   for (int d0 = 0; d0 < NQ; ++d0) { const int cb = kcolB + (d0 * 16 + hi * 8) * 2;
;     bf16x8 b0 = *reinterpret_cast<const bf16x8*>(Ks + KSWZ(r32, cb));
;     bf16x8 b1 = *reinterpret_cast<const bf16x8*>(Ks + KSWZ(32 + r32, cb));
;     p0 = __builtin_amdgcn_mfma_f32_32x32x16_bf16(b0, qr[d0], p0, 0, 0, 0);
;     p1 = __builtin_amdgcn_mfma_f32_32x32x16_bf16(b1, qr[d0], p1, 0, 0, 0); }
; }
; __device__ __forceinline__ void qkt0(f32x16& p0, f32x16& p1, const char* Ks, const char* Qs, int r32, int hi, int kcolB, const f32x16& init) {
; #pragma unroll
;   for (int d0 = 0; d0 < 4; ++d0) { const int cb = kcolB + (d0 * 16 + hi * 8) * 2;
;     bf16x8 b0 = *reinterpret_cast<const bf16x8*>(Ks + KSWZ(r32, cb));
;     bf16x8 b1 = *reinterpret_cast<const bf16x8*>(Ks + KSWZ(32 + r32, cb));
;     bf16x8 qf = *reinterpret_cast<const bf16x8*>(Qs + r32 * 128 + (((2 * d0 + hi) ^ (r32 & 7)) << 4));
;     if (d0 == 0) { p0 = __builtin_amdgcn_mfma_f32_32x32x16_bf16(b0, qf, init, 0, 0, 0); p1 = __builtin_amdgcn_mfma_f32_32x32x16_bf16(b1, qf, init, 0, 0, 0); }
;     else { p0 = __builtin_amdgcn_mfma_f32_32x32x16_bf16(b0, qf, p0, 0, 0, 0); p1 = __builtin_amdgcn_mfma_f32_32x32x16_bf16(b1, qf, p1, 0, 0, 0); } }
; }
.Lstag_a:
	s_add_i32 s34, s59, 0
	v_add_u32_e32 v112, s34, v193
	v_add_u32_e32 v116, s34, v194
	ds_read_b128 v[112:115], v112 offset:16384
	ds_read_b128 v[202:205], v181
	ds_read_b128 v[206:209], v180
	ds_read_b128 v[210:213], v116 offset:16384
	v_exp_f32_e32 v234, v96
	v_add_f32_e32 v254, 0, v161
	s_waitcnt lgkmcnt(2)
	v_mfma_f32_32x32x16_bf16 v[128:143], v[112:115], v[202:205], v[80:95]
	v_add_u32_e32 v112, s34, v197
	v_add_u32_e32 v113, s34, v195
	v_add_f32_e32 v255, 0, v163
	ds_read_b128 v[214:217], v112 offset:16384
	ds_read_b128 v[218:221], v113 offset:16384
	v_add_f32_e32 v254, v159, v254
	v_add_f32_e32 v255, v162, v255
	v_add_f32_e32 v254, v157, v254
	s_waitcnt lgkmcnt(2)
	v_mfma_f32_32x32x16_bf16 v[112:127], v[210:213], v[202:205], v[80:95]
	v_add_f32_e32 v255, v160, v255
	v_add_f32_e32 v254, v156, v254
	v_add_f32_e32 v255, v158, v255
	v_add_f32_e32 v254, v153, v254
	v_add_f32_e32 v255, v155, v255
	v_add_f32_e32 v254, v151, v254
	v_add_f32_e32 v255, v154, v255
	s_waitcnt lgkmcnt(0)
	v_mfma_f32_32x32x16_bf16 v[128:143], v[218:221], v[206:209], v[128:143]
	v_add_f32_e32 v254, v149, v254
	v_add_u32_e32 v201, s34, v199
	v_add_u32_e32 v210, s34, v196
	v_exp_f32_e32 v235, v97
	v_add_f32_e32 v255, v152, v255
	ds_read_b128 v[202:205], v201 offset:16384
	ds_read_b128 v[210:213], v210 offset:16384
	ds_read_b128 v[222:225], v179
	ds_read_b128 v[226:229], v178
	v_exp_f32_e32 v236, v98
	v_mfma_f32_32x32x16_bf16 v[112:127], v[214:217], v[206:209], v[112:127]
	v_add_f32_e32 v254, v148, v254
	v_exp_f32_e32 v237, v99
	v_add_f32_e32 v255, v150, v255
	v_exp_f32_e32 v238, v100
	v_add_f32_e32 v254, v234, v254
	v_exp_f32_e32 v239, v101
	v_add_f32_e32 v255, v235, v255
	v_exp_f32_e32 v206, v102
	s_waitcnt lgkmcnt(1)
	v_mfma_f32_32x32x16_bf16 v[128:143], v[210:213], v[222:225], v[128:143]
	v_add_f32_e32 v254, v236, v254
	v_exp_f32_e32 v207, v103
	v_add_f32_e32 v255, v237, v255
	v_add_u32_e32 v201, s34, v200
	v_add_u32_e32 v230, s34, v198
	v_exp_f32_e32 v208, v104
	v_add_f32_e32 v254, v238, v254
	v_mfma_f32_32x32x16_bf16 v[112:127], v[202:205], v[222:225], v[112:127]
	ds_read_b128 v[218:221], v201 offset:16384
	ds_read_b128 v[230:233], v230 offset:16384
	v_exp_f32_e32 v209, v105
	v_add_f32_e32 v255, v239, v255
	v_exp_f32_e32 v214, v106
	v_add_f32_e32 v254, v206, v254
	v_exp_f32_e32 v215, v107
	v_add_f32_e32 v255, v207, v255
	v_exp_f32_e32 v216, v108
	v_add_f32_e32 v254, v208, v254
	v_exp_f32_e32 v210, v109
	v_add_f32_e32 v255, v209, v255
	v_exp_f32_e32 v211, v110
	s_waitcnt lgkmcnt(0)
	v_mfma_f32_32x32x16_bf16 v[128:143], v[230:233], v[226:229], v[128:143]
	v_add_f32_e32 v254, v214, v254
	v_exp_f32_e32 v111, v111
	v_add_f32_e32 v255, v215, v255
	v_add_f32_e32 v254, v216, v254
	v_add_f32_e32 v255, v210, v255
	v_add_f32_e32 v254, v211, v254
	v_add_f32_e32 v255, v111, v255
	v_add_f32_e32 v201, v254, v255
	v_mfma_f32_32x32x16_bf16 v[112:127], v[218:221], v[226:229], v[112:127]
	v_mov_b32_e32 v202, v201
	s_nop 1
	v_permlane32_swap_b32_e32 v201, v202
	v_cvt_pk_bf16_f32 v96, v161, v163
	v_cvt_pk_bf16_f32 v97, v159, v162
	v_cvt_pk_bf16_f32 v98, v157, v160
	v_cvt_pk_bf16_f32 v99, v156, v158
	v_cvt_pk_bf16_f32 v100, v153, v155
	v_cvt_pk_bf16_f32 v101, v151, v154
	v_cvt_pk_bf16_f32 v102, v149, v152
	v_cvt_pk_bf16_f32 v103, v148, v150
	v_cvt_pk_bf16_f32 v104, v234, v235
	v_cvt_pk_bf16_f32 v105, v236, v237
	v_cvt_pk_bf16_f32 v106, v238, v239
	v_cvt_pk_bf16_f32 v107, v206, v207
	v_cvt_pk_bf16_f32 v108, v208, v209
	v_cvt_pk_bf16_f32 v109, v214, v215
	v_cvt_pk_bf16_f32 v110, v216, v210
	v_cvt_pk_bf16_f32 v111, v211, v111
	s_nop 0
	v_permlane32_swap_b32_e32 v96, v98
	v_permlane32_swap_b32_e32 v97, v99
	v_permlane32_swap_b32_e32 v100, v102
	v_permlane32_swap_b32_e32 v101, v103
	v_permlane32_swap_b32_e32 v104, v106
	v_permlane32_swap_b32_e32 v105, v107
	v_permlane32_swap_b32_e32 v108, v110
	v_permlane32_swap_b32_e32 v109, v111
	v_add_u32_e32 v203, s36, v175
	ds_read_b64_tr_b16 v[148:149], v203 offset:0
	ds_read_b64_tr_b16 v[150:151], v203 offset:0x800
	ds_read_b64_tr_b16 v[152:153], v203 offset:0x1000
	ds_read_b64_tr_b16 v[154:155], v203 offset:0x1800
	ds_read_b64_tr_b16 v[156:157], v203 offset:0x2000
	ds_read_b64_tr_b16 v[158:159], v203 offset:0x2800
	ds_read_b64_tr_b16 v[160:161], v203 offset:0x3000
	ds_read_b64_tr_b16 v[162:163], v203 offset:0x3800
	s_add_i32 s34, s58, 1
	s_waitcnt lgkmcnt(0)
; __device__ __forceinline__ void pv_d0(f32x16* o, int vb, bf16x8 pa0, bf16x8 pa1, bf16x8 pa2, bf16x8 pa3) {
;   s16x4 la[4], ha[4];
;   rd8<0>(la, ha, vb); WAITDEP(0, la, ha); mma4(o[0], la, ha, pa0, pa1, pa2, pa3);
;   rd8<1>(la, ha, vb); WAITDEP(0, la, ha); mma4(o[1], la, ha, pa0, pa1, pa2, pa3);
;   rd8<2>(la, ha, vb); WAITDEP(0, la, ha); mma4(o[2], la, ha, pa0, pa1, pa2, pa3);
;   rd8<3>(la, ha, vb); WAITDEP(0, la, ha); mma4(o[3], la, ha, pa0, pa1, pa2, pa3);
; }
; template <int MODE>
; __device__ __forceinline__ void attn_unit(bf16r* P0, const bf16r* __restrict__ PKV, int rowbase, int seqL, int h, int blk, float lam,
;                                           const float* __restrict__ subg, const float* __restrict__ tsrc, char* lds) {
;   constexpr int NQ = (MODE == 0) ? 4 : 8;
;   int tid_ = threadIdx.x; asm volatile("" : "+v"(tid_));
;   const int tid = tid_, wid = __builtin_amdgcn_readfirstlane(tid >> 6), lane = tid & 63, r32 = lane & 31, hi = lane >> 5;
;   float* ws = (float*)(lds + OFF_WS) + wid * 64; float* li_l = ws; float* al_l = ws + 32;
;   float* tb = (float*)(lds + OFF_TB);
;   int qrow, kcolB, tbase, NT, colbase, gr = 0, rs = 0, qc = 0, cmap = 0;
;   float bL = 0.f, bR = 0.f;
;   if constexpr (MODE == 0) {
;     cmap = wid >> 2; qrow = blk * 128 + (wid & 3) * 32; kcolB = cmap * 128; tbase = 0; NT = seqL / KVBLK; colbase = h * 128;
;     bL = tsrc[15 * 8 + h] * LOG2E; bR = tsrc[31 * 8 + h] * LOG2E;
;     { const int rel = tid - 256, n = rel < 0 ? -rel : rel;
;       int bk = n < 8 ? n : min(15, 8 + (31 - __clz((n * n) >> 6))); if (rel > 0) bk += 16;
;       tb[tid] = tsrc[bk * 8 + h] * LOG2E; }
;   } else {
;     const int rows = seqL / 64; qrow = blk * 256 + wid * 32; kcolB = 0; colbase = 1024 + h * 128; NT = 12;
;     const int rs0 = min(max(blk * 4 - 4, 0), rows - 8); tbase = min(rs0, rows - 12);
;     gr = blk * 4 + (wid >> 1); rs = min(max(gr - 4, 0), rows - 8); qc = (wid & 1) * 32 + r32;
;     for (int i = tid; i < 15 * 128; i += 512) { const int dr = i >> 7, dc = (i & 127) - 48; tb[i] = (dc >= 0 && dc < 31) ? tsrc[(h * 15 + dr) * 31 + dc] * LOG2E : 0.f; }
;   }
;   const bf16r* Qw = P0 + (size_t)(rowbase + qrow + r32) * LD + colbase + (MODE == 0 ? cmap * 64 : 0) + hi * 8;
;   const bf16r* Kh = PKV + (size_t)rowbase * LD + h * 128; const bf16r* Vh = Kh + 1024;
;   float m_reg = -1e30f, l_reg = 0; f32x16 o[4] = {};
	s_add_i32 s60, s37, 0
	v_mfma_f32_32x32x16_bf16 v[64:79], v[96:99], v[148:151], v[64:79]
	ds_read_b64_tr_b16 v[148:149], v203 offset:0x200
	ds_read_b64_tr_b16 v[150:151], v203 offset:0xa00
	ds_read_b64_tr_b16 v[204:205], v203 offset:0x1200
	ds_read_b64_tr_b16 v[206:207], v203 offset:0x1a00
	ds_read_b64_tr_b16 v[208:209], v203 offset:0x2200
	ds_read_b64_tr_b16 v[210:211], v203 offset:0x2a00
	ds_read_b64_tr_b16 v[212:213], v203 offset:0x3200
	v_mfma_f32_32x32x16_bf16 v[64:79], v[100:103], v[152:155], v[64:79]
	ds_read_b64_tr_b16 v[214:215], v203 offset:0x3a00
	s_min_i32 s34, s34, s39
	s_waitcnt lgkmcnt(0)
	s_cmp_ge_i32 s34, s56
	s_cselect_b32 s35, s57, 0
	s_add_i32 s35, s35, s34
	s_lshl_b32 s34, s35, 6
	v_mfma_f32_32x32x16_bf16 v[64:79], v[104:107], v[156:159], v[64:79]
	v_mfma_f32_32x32x16_bf16 v[48:63], v[96:99], v[148:151], v[48:63]
	ds_read_b64_tr_b16 v[148:149], v203 offset:0x400
	ds_read_b64_tr_b16 v[150:151], v203 offset:0xc00
	ds_read_b64_tr_b16 v[152:153], v203 offset:0x1400
	ds_read_b64_tr_b16 v[154:155], v203 offset:0x1c00
	v_mfma_f32_32x32x16_bf16 v[64:79], v[108:111], v[160:163], v[64:79]
	ds_read_b64_tr_b16 v[160:161], v203 offset:0x2400
	ds_read_b64_tr_b16 v[162:163], v203 offset:0x2c00
	v_mfma_f32_32x32x16_bf16 v[48:63], v[100:103], v[204:207], v[48:63]
	ds_read_b64_tr_b16 v[204:205], v203 offset:0x3400
	ds_read_b64_tr_b16 v[206:207], v203 offset:0x3c00
	s_nop 0
	s_waitcnt lgkmcnt(0)
	ds_read_b64_tr_b16 v[216:217], v203 offset:0x600
	ds_read_b64_tr_b16 v[218:219], v203 offset:0xe00
	s_nop 0
	v_mfma_f32_32x32x16_bf16 v[32:47], v[96:99], v[148:151], v[32:47]
	v_add_u32_e32 v148, s34, v182
	v_add_u32_e32 v150, s34, v188
	v_ashrrev_i32_e32 v149, 31, v148
	v_ashrrev_i32_e32 v151, 31, v150
	v_lshlrev_b64 v[148:149], 12, v[148:149]
	v_lshlrev_b64 v[150:151], 12, v[150:151]
	v_or_b32_e32 v148, v148, v168
	v_mfma_f32_32x32x16_bf16 v[48:63], v[104:107], v[208:211], v[48:63]
	ds_read_b64_tr_b16 v[208:209], v203 offset:0x1600
	ds_read_b64_tr_b16 v[210:211], v203 offset:0x1e00
	ds_read_b64_tr_b16 v[220:221], v203 offset:0x2600
	ds_read_b64_tr_b16 v[222:223], v203 offset:0x2e00
	ds_read_b64_tr_b16 v[224:225], v203 offset:0x3600
	ds_read_b64_tr_b16 v[226:227], v203 offset:0x3e00
	v_or_b32_e32 v150, v150, v168
	v_mfma_f32_32x32x16_bf16 v[32:47], v[100:103], v[152:155], v[32:47]
	s_waitcnt lgkmcnt(0)
	s_waitcnt vmcnt(0)
	v_lshl_add_u64 v[148:149], s[30:31], 0, v[148:149]
	v_lshl_add_u64 v[152:153], s[30:31], 0, v[150:151]
	global_load_dwordx4 v[156:159], v[148:149], off offset:2048
	s_nop 0
	global_load_dwordx4 v[148:151], v[148:149], off
	v_add_u32_e32 v203, s60, v183
	v_mfma_f32_32x32x16_bf16 v[32:47], v[104:107], v[160:163], v[32:47]
	global_load_dwordx4 v[160:163], v[152:153], off offset:2048
	s_nop 0
	global_load_dwordx4 v[152:155], v[152:153], off
	s_waitcnt vmcnt(7)
	ds_write_b128 v203, v[6:9]
	v_add_u32_e32 v6, s60, v189
	s_waitcnt vmcnt(5)
	ds_write_b128 v6, v[144:147]
	v_add_u32_e32 v6, s60, v190
	ds_write_b128 v6, v[2:5] offset:16384
	v_add_u32_e32 v2, s60, v191
	v_mfma_f32_32x32x16_bf16 v[16:31], v[96:99], v[216:219], v[16:31]
	s_waitcnt vmcnt(4)
	ds_write_b128 v2, v[10:13] offset:16384
	v_max_f32_e32 v2, v129, v129
	v_max_f32_e32 v3, v128, v128
	v_max_f32_e32 v2, v3, v2
	v_max3_f32 v2, v2, v130, v131
	v_max3_f32 v2, v2, v132, v133
	v_max3_f32 v2, v2, v134, v135
	v_mfma_f32_32x32x16_bf16 v[16:31], v[100:103], v[208:211], v[16:31]
	v_max3_f32 v2, v2, v136, v137
	v_max3_f32 v2, v2, v138, v139
	v_max3_f32 v2, v2, v140, v141
	v_max3_f32 v2, v2, v142, v143
	v_max3_f32 v2, v2, v112, v113
	v_max3_f32 v2, v2, v114, v115
	v_max3_f32 v2, v2, v116, v117
	v_mfma_f32_32x32x16_bf16 v[16:31], v[104:107], v[220:223], v[16:31]
	v_max3_f32 v2, v2, v118, v119
	v_max3_f32 v2, v2, v120, v121
	v_max3_f32 v2, v2, v122, v123
	v_max3_f32 v2, v2, v124, v125
	v_max3_f32 v2, v2, v126, v127
	v_mov_b32_e32 v3, v2
	s_nop 1
	v_permlane32_swap_b32_e32 v2, v3
	v_mfma_f32_32x32x16_bf16 v[48:63], v[108:111], v[212:215], v[48:63]
	v_max_f32_e32 v3, v3, v3
	v_max_f32_e32 v2, v2, v2
	v_max_f32_e32 v2, v2, v3
	v_cmp_ge_f32_e32 vcc, s49, v2
	s_cmp_eq_u64 vcc, exec
	v_mov_b32_e32 v203, 1.0
	v_mfma_f32_32x32x16_bf16 v[32:47], v[108:111], v[204:207], v[32:47]
	v_mfma_f32_32x32x16_bf16 v[16:31], v[108:111], v[224:227], v[16:31]
	s_cbranch_scc0 .LBB0_229

; __device__ __forceinline__ void finishSM(f32x16& p0, f32x16& p1, float alpha, float& l_reg, bf16x8& pa0, bf16x8& pa1, bf16x8& pa2, bf16x8& pa3) {
; #pragma unroll
;   for (int r = 0; r < 16; ++r) p1[r] = __builtin_amdgcn_exp2f(p1[r]);
;   float ps = 0;
; #pragma unroll
;   for (int r = 0; r < 16; ++r) ps += p0[r];
; #pragma unroll
;   for (int r = 0; r < 16; ++r) ps += p1[r];
;   { auto rr = __builtin_amdgcn_permlane32_swap(__float_as_uint(ps), __float_as_uint(ps), false, false);
;     ps = __uint_as_float(rr[0]) + __uint_as_float(rr[1]); }
;   l_reg = l_reg * alpha + ps;
;     ...
;   PK4(p0, 0, pa0); PK4(p0, 8, pa1); PK4(p1, 0, pa2); PK4(p1, 8, pa3);
;     ...
; }
; template <int NQ> __device__ __forceinline__ void qkt(f32x16& p0, f32x16& p1, const char* Ks, const bf16x8* qr, int r32, int hi, int kcolB) {
;   p0 = f32x16{}; p1 = f32x16{};
; #pragma unroll
;   for (int d0 = 0; d0 < NQ; ++d0) { const int cb = kcolB + (d0 * 16 + hi * 8) * 2;
;     bf16x8 b0 = *reinterpret_cast<const bf16x8*>(Ks + KSWZ(r32, cb));
;     bf16x8 b1 = *reinterpret_cast<const bf16x8*>(Ks + KSWZ(32 + r32, cb));
;     p0 = __builtin_amdgcn_mfma_f32_32x32x16_bf16(b0, qr[d0], p0, 0, 0, 0);
;     p1 = __builtin_amdgcn_mfma_f32_32x32x16_bf16(b1, qr[d0], p1, 0, 0, 0); }
; }
; __device__ __forceinline__ void qkt0(f32x16& p0, f32x16& p1, const char* Ks, const char* Qs, int r32, int hi, int kcolB, const f32x16& init) {
; #pragma unroll
;   for (int d0 = 0; d0 < 4; ++d0) { const int cb = kcolB + (d0 * 16 + hi * 8) * 2;
;     bf16x8 b0 = *reinterpret_cast<const bf16x8*>(Ks + KSWZ(r32, cb));
;     bf16x8 b1 = *reinterpret_cast<const bf16x8*>(Ks + KSWZ(32 + r32, cb));
;     bf16x8 qf = *reinterpret_cast<const bf16x8*>(Qs + r32 * 128 + (((2 * d0 + hi) ^ (r32 & 7)) << 4));
;     if (d0 == 0) { p0 = __builtin_amdgcn_mfma_f32_32x32x16_bf16(b0, qf, init, 0, 0, 0); p1 = __builtin_amdgcn_mfma_f32_32x32x16_bf16(b1, qf, init, 0, 0, 0); }
;     else { p0 = __builtin_amdgcn_mfma_f32_32x32x16_bf16(b0, qf, p0, 0, 0, 0); p1 = __builtin_amdgcn_mfma_f32_32x32x16_bf16(b1, qf, p1, 0, 0, 0); } }
; }
.Lstag_b:
	v_exp_f32_e32 v224, v128
	v_exp_f32_e32 v225, v129
	v_exp_f32_e32 v226, v130
	v_exp_f32_e32 v227, v131
	v_exp_f32_e32 v228, v132
	v_exp_f32_e32 v229, v133
	v_exp_f32_e32 v230, v134
	v_exp_f32_e32 v231, v135
	v_exp_f32_e32 v232, v136
	v_exp_f32_e32 v233, v137
	v_exp_f32_e32 v234, v138
	v_exp_f32_e32 v235, v139
	v_exp_f32_e32 v236, v140
	v_exp_f32_e32 v237, v141
	v_exp_f32_e32 v238, v142
	v_exp_f32_e32 v239, v143
	v_add_u32_e32 v2, s60, v193
	ds_read_b128 v[2:5], v2 offset:16384
	ds_read_b128 v[6:9], v181
	v_add_u32_e32 v96, s60, v194
	ds_read_b128 v[10:13], v180
	v_add_u32_e32 v97, s60, v195
	v_add_u32_e32 v208, s60, v199
	s_waitcnt lgkmcnt(1)
	v_mfma_f32_32x32x16_bf16 v[128:143], v[2:5], v[6:9], v[80:95]
	ds_read_b128 v[2:5], v96 offset:16384
	v_add_u32_e32 v96, s60, v197
	ds_read_b128 v[144:147], v96 offset:16384
	ds_read_b128 v[204:207], v97 offset:16384
	v_add_u32_e32 v209, s60, v196
	v_exp_f32_e32 v240, v114
	v_exp_f32_e32 v241, v115
	v_exp_f32_e32 v242, v116
	s_waitcnt lgkmcnt(0)
	v_mfma_f32_32x32x16_bf16 v[128:143], v[204:207], v[10:13], v[128:143]
	v_exp_f32_e32 v206, v112
	v_exp_f32_e32 v207, v113
	v_exp_f32_e32 v243, v117
	v_exp_f32_e32 v244, v118
	v_add_u32_e32 v216, s60, v200
	v_add_u32_e32 v220, s60, v198
	v_mfma_f32_32x32x16_bf16 v[96:111], v[2:5], v[6:9], v[80:95]
	ds_read_b128 v[2:5], v208 offset:16384
	ds_read_b128 v[6:9], v209 offset:16384
	ds_read_b128 v[208:211], v179
	ds_read_b128 v[212:215], v178
	ds_read_b128 v[216:219], v216 offset:16384
	ds_read_b128 v[220:223], v220 offset:16384
	v_cvt_pk_bf16_f32 v116, v224, v225
	v_cvt_pk_bf16_f32 v117, v226, v227
	v_cvt_pk_bf16_f32 v118, v228, v229
	s_nop 0
	v_permlane32_swap_b32_e32 v116, v118
	v_mfma_f32_32x32x16_bf16 v[96:111], v[144:147], v[10:13], v[96:111]
	v_exp_f32_e32 v10, v119
	v_exp_f32_e32 v11, v120
	v_exp_f32_e32 v12, v121
	v_exp_f32_e32 v13, v122
	v_exp_f32_e32 v144, v123
	v_exp_f32_e32 v145, v124
	v_exp_f32_e32 v146, v125
	s_waitcnt lgkmcnt(3)
	v_mfma_f32_32x32x16_bf16 v[128:143], v[6:9], v[208:211], v[128:143]
	v_add_f32_e32 v254, 0, v224
	v_add_f32_e32 v255, 0, v225
	v_add_f32_e32 v254, v226, v254
	v_add_f32_e32 v255, v227, v255
	v_add_f32_e32 v254, v228, v254
	v_exp_f32_e32 v6, v126
	v_exp_f32_e32 v7, v127
	v_mfma_f32_32x32x16_bf16 v[96:111], v[2:5], v[208:211], v[96:111]
	v_add_f32_e32 v255, v229, v255
	v_add_f32_e32 v254, v230, v254
	v_add_f32_e32 v255, v231, v255
	v_add_f32_e32 v254, v232, v254
	v_add_f32_e32 v255, v233, v255
	v_add_f32_e32 v254, v234, v254
	v_add_f32_e32 v255, v235, v255
	v_add_f32_e32 v254, v236, v254
	v_add_f32_e32 v255, v237, v255
	v_add_f32_e32 v254, v238, v254
	v_add_f32_e32 v255, v239, v255
	v_add_f32_e32 v254, v206, v254
	v_add_f32_e32 v255, v207, v255
	v_add_f32_e32 v254, v240, v254
	v_add_f32_e32 v255, v241, v255
	v_add_f32_e32 v254, v242, v254
	v_add_f32_e32 v255, v243, v255
	v_add_f32_e32 v254, v244, v254
	v_add_f32_e32 v255, v10, v255
	v_add_f32_e32 v254, v11, v254
	v_add_f32_e32 v255, v12, v255
	s_waitcnt lgkmcnt(0)
	v_mfma_f32_32x32x16_bf16 v[128:143], v[220:223], v[212:215], v[128:143]
	v_add_f32_e32 v254, v13, v254
	v_add_f32_e32 v255, v144, v255
	v_add_f32_e32 v254, v145, v254
	v_add_f32_e32 v255, v146, v255
	v_add_f32_e32 v254, v6, v254
	v_add_f32_e32 v255, v7, v255
	v_add_f32_e32 v204, v254, v255
	v_mov_b32_e32 v205, v204
	v_mfma_f32_32x32x16_bf16 v[96:111], v[216:219], v[212:215], v[96:111]
	v_cvt_pk_bf16_f32 v119, v230, v231
	v_cvt_pk_bf16_f32 v112, v232, v233
	v_cvt_pk_bf16_f32 v113, v234, v235
	v_cvt_pk_bf16_f32 v114, v236, v237
	v_cvt_pk_bf16_f32 v115, v238, v239
	s_nop 0
	v_permlane32_swap_b32_e32 v204, v205
	v_permlane32_swap_b32_e32 v112, v114
	v_permlane32_swap_b32_e32 v113, v115
	v_cvt_pk_bf16_f32 v120, v206, v207
	v_cvt_pk_bf16_f32 v121, v240, v241
	v_cvt_pk_bf16_f32 v122, v242, v243
	v_cvt_pk_bf16_f32 v123, v244, v10
	v_cvt_pk_bf16_f32 v124, v11, v12
	v_cvt_pk_bf16_f32 v125, v13, v144
	v_cvt_pk_bf16_f32 v126, v145, v146
	v_cvt_pk_bf16_f32 v127, v6, v7
	v_permlane32_swap_b32_e32 v117, v119
	v_permlane32_swap_b32_e32 v120, v122
	v_permlane32_swap_b32_e32 v121, v123
	v_permlane32_swap_b32_e32 v124, v126
	v_permlane32_swap_b32_e32 v125, v127
	v_add_u32_e32 v230, s59, v175
	ds_read_b64_tr_b16 v[2:3], v230 offset:0
	ds_read_b64_tr_b16 v[4:5], v230 offset:0x800
	ds_read_b64_tr_b16 v[6:7], v230 offset:0x1000
	ds_read_b64_tr_b16 v[8:9], v230 offset:0x1800
	ds_read_b64_tr_b16 v[10:11], v230 offset:0x2000
	ds_read_b64_tr_b16 v[12:13], v230 offset:0x2800
	ds_read_b64_tr_b16 v[144:145], v230 offset:0x3000
	ds_read_b64_tr_b16 v[146:147], v230 offset:0x3800
	s_add_i32 s58, s58, 2
	s_waitcnt lgkmcnt(0)
; __device__ __forceinline__ void pv_d0(f32x16* o, int vb, bf16x8 pa0, bf16x8 pa1, bf16x8 pa2, bf16x8 pa3) {
;   s16x4 la[4], ha[4];
;   rd8<0>(la, ha, vb); WAITDEP(0, la, ha); mma4(o[0], la, ha, pa0, pa1, pa2, pa3);
;   rd8<1>(la, ha, vb); WAITDEP(0, la, ha); mma4(o[1], la, ha, pa0, pa1, pa2, pa3);
;   rd8<2>(la, ha, vb); WAITDEP(0, la, ha); mma4(o[2], la, ha, pa0, pa1, pa2, pa3);
;   rd8<3>(la, ha, vb); WAITDEP(0, la, ha); mma4(o[3], la, ha, pa0, pa1, pa2, pa3);
; }
; template <int MODE>
; __device__ __forceinline__ void attn_unit(bf16r* P0, const bf16r* __restrict__ PKV, int rowbase, int seqL, int h, int blk, float lam,
;                                           const float* __restrict__ subg, const float* __restrict__ tsrc, char* lds) {
;   constexpr int NQ = (MODE == 0) ? 4 : 8;
;   int tid_ = threadIdx.x; asm volatile("" : "+v"(tid_));
;   const int tid = tid_, wid = __builtin_amdgcn_readfirstlane(tid >> 6), lane = tid & 63, r32 = lane & 31, hi = lane >> 5;
;   float* ws = (float*)(lds + OFF_WS) + wid * 64; float* li_l = ws; float* al_l = ws + 32;
;   float* tb = (float*)(lds + OFF_TB);
;   int qrow, kcolB, tbase, NT, colbase, gr = 0, rs = 0, qc = 0, cmap = 0;
;   float bL = 0.f, bR = 0.f;
;   if constexpr (MODE == 0) {
;     cmap = wid >> 2; qrow = blk * 128 + (wid & 3) * 32; kcolB = cmap * 128; tbase = 0; NT = seqL / KVBLK; colbase = h * 128;
;     bL = tsrc[15 * 8 + h] * LOG2E; bR = tsrc[31 * 8 + h] * LOG2E;
;     { const int rel = tid - 256, n = rel < 0 ? -rel : rel;
;       int bk = n < 8 ? n : min(15, 8 + (31 - __clz((n * n) >> 6))); if (rel > 0) bk += 16;
;       tb[tid] = tsrc[bk * 8 + h] * LOG2E; }
;   } else {
;     const int rows = seqL / 64; qrow = blk * 256 + wid * 32; kcolB = 0; colbase = 1024 + h * 128; NT = 12;
;     const int rs0 = min(max(blk * 4 - 4, 0), rows - 8); tbase = min(rs0, rows - 12);
;     gr = blk * 4 + (wid >> 1); rs = min(max(gr - 4, 0), rows - 8); qc = (wid & 1) * 32 + r32;
;     for (int i = tid; i < 15 * 128; i += 512) { const int dr = i >> 7, dc = (i & 127) - 48; tb[i] = (dc >= 0 && dc < 31) ? tsrc[(h * 15 + dr) * 31 + dc] * LOG2E : 0.f; }
;   }
;   const bf16r* Qw = P0 + (size_t)(rowbase + qrow + r32) * LD + colbase + (MODE == 0 ? cmap * 64 : 0) + hi * 8;
;   const bf16r* Kh = PKV + (size_t)rowbase * LD + h * 128; const bf16r* Vh = Kh + 1024;
;   float m_reg = -1e30f, l_reg = 0; f32x16 o[4] = {};
	s_add_i32 s34, s36, 0
	v_mfma_f32_32x32x16_bf16 v[64:79], v[116:119], v[2:5], v[64:79]
	ds_read_b64_tr_b16 v[2:3], v230 offset:0x200
	ds_read_b64_tr_b16 v[4:5], v230 offset:0xa00
	ds_read_b64_tr_b16 v[206:207], v230 offset:0x1200
	ds_read_b64_tr_b16 v[208:209], v230 offset:0x1a00
	ds_read_b64_tr_b16 v[210:211], v230 offset:0x2200
	ds_read_b64_tr_b16 v[212:213], v230 offset:0x2a00
	ds_read_b64_tr_b16 v[214:215], v230 offset:0x3200
	v_mfma_f32_32x32x16_bf16 v[64:79], v[112:115], v[6:9], v[64:79]
	ds_read_b64_tr_b16 v[216:217], v230 offset:0x3a00
	s_min_i32 s35, s58, s39
	s_waitcnt lgkmcnt(0)
	s_cmp_ge_i32 s35, s56
	s_cselect_b32 s60, s57, 0
	s_add_i32 s60, s60, s35
	s_lshl_b32 s35, s60, 6
	v_mfma_f32_32x32x16_bf16 v[48:63], v[116:119], v[2:5], v[48:63]
	ds_read_b64_tr_b16 v[2:3], v230 offset:0x400
	ds_read_b64_tr_b16 v[4:5], v230 offset:0xc00
	ds_read_b64_tr_b16 v[6:7], v230 offset:0x1400
	ds_read_b64_tr_b16 v[8:9], v230 offset:0x1c00
	v_mfma_f32_32x32x16_bf16 v[64:79], v[120:123], v[10:13], v[64:79]
	ds_read_b64_tr_b16 v[10:11], v230 offset:0x2400
	ds_read_b64_tr_b16 v[12:13], v230 offset:0x2c00
	v_mfma_f32_32x32x16_bf16 v[48:63], v[112:115], v[206:209], v[48:63]
	ds_read_b64_tr_b16 v[206:207], v230 offset:0x3400
	ds_read_b64_tr_b16 v[208:209], v230 offset:0x3c00
	s_nop 0
	s_waitcnt lgkmcnt(0)
	ds_read_b64_tr_b16 v[218:219], v230 offset:0x600
	ds_read_b64_tr_b16 v[220:221], v230 offset:0xe00
	s_nop 0
	v_mfma_f32_32x32x16_bf16 v[32:47], v[116:119], v[2:5], v[32:47]
	v_add_u32_e32 v2, s35, v182
	v_add_u32_e32 v4, s35, v188
	v_ashrrev_i32_e32 v3, 31, v2
	v_ashrrev_i32_e32 v5, 31, v4
	v_lshlrev_b64 v[2:3], 12, v[2:3]
	v_lshlrev_b64 v[4:5], 12, v[4:5]
	v_or_b32_e32 v2, v2, v168
	v_mfma_f32_32x32x16_bf16 v[48:63], v[120:123], v[210:213], v[48:63]
	ds_read_b64_tr_b16 v[210:211], v230 offset:0x1600
	ds_read_b64_tr_b16 v[212:213], v230 offset:0x1e00
	ds_read_b64_tr_b16 v[222:223], v230 offset:0x2600
	ds_read_b64_tr_b16 v[224:225], v230 offset:0x2e00
	ds_read_b64_tr_b16 v[226:227], v230 offset:0x3600
	ds_read_b64_tr_b16 v[228:229], v230 offset:0x3e00
	v_or_b32_e32 v4, v4, v168
	v_mfma_f32_32x32x16_bf16 v[32:47], v[112:115], v[6:9], v[32:47]
	s_waitcnt lgkmcnt(0)
	s_waitcnt vmcnt(0)
	v_lshl_add_u64 v[2:3], s[30:31], 0, v[2:3]
	v_mfma_f32_32x32x16_bf16 v[48:63], v[124:127], v[214:217], v[48:63]
	v_lshl_add_u64 v[214:215], s[30:31], 0, v[4:5]
	global_load_dwordx4 v[6:9], v[2:3], off offset:2048
	s_nop 0
	global_load_dwordx4 v[2:5], v[2:3], off
	v_mfma_f32_32x32x16_bf16 v[64:79], v[124:127], v[144:147], v[64:79]
	v_mfma_f32_32x32x16_bf16 v[32:47], v[120:123], v[10:13], v[32:47]
	global_load_dwordx4 v[144:147], v[214:215], off offset:2048
	global_load_dwordx4 v[10:13], v[214:215], off
	v_add_u32_e32 v214, s34, v183
	s_waitcnt vmcnt(7)
	ds_write_b128 v214, v[156:159]
	v_add_u32_e32 v156, s34, v189
	s_waitcnt vmcnt(5)
	ds_write_b128 v156, v[160:163]
	v_add_u32_e32 v156, s34, v190
	ds_write_b128 v156, v[148:151] offset:16384
	v_mfma_f32_32x32x16_bf16 v[16:31], v[116:119], v[218:221], v[16:31]
	v_add_u32_e32 v148, s34, v191
	s_waitcnt vmcnt(4)
	ds_write_b128 v148, v[152:155] offset:16384
	v_max_f32_e32 v148, v129, v129
	v_max_f32_e32 v149, v128, v128
	v_max_f32_e32 v148, v149, v148
	v_max3_f32 v148, v148, v130, v131
	v_max3_f32 v148, v148, v132, v133
	v_mfma_f32_32x32x16_bf16 v[16:31], v[112:115], v[210:213], v[16:31]
	v_max3_f32 v116, v148, v134, v135
	v_max3_f32 v116, v116, v136, v137
	v_max3_f32 v116, v116, v138, v139
	v_max3_f32 v116, v116, v140, v141
	v_max3_f32 v116, v116, v142, v143
	v_max3_f32 v116, v116, v96, v97
	v_max3_f32 v116, v116, v98, v99
	v_mfma_f32_32x32x16_bf16 v[16:31], v[120:123], v[222:225], v[16:31]
	v_max3_f32 v112, v116, v100, v101
	v_max3_f32 v112, v112, v102, v103
	v_max3_f32 v112, v112, v104, v105
	v_max3_f32 v112, v112, v106, v107
	v_max3_f32 v112, v112, v108, v109
	v_max3_f32 v112, v112, v110, v111
	v_mov_b32_e32 v113, v112
	v_mfma_f32_32x32x16_bf16 v[32:47], v[124:127], v[206:209], v[32:47]
	s_nop 0
	v_permlane32_swap_b32_e32 v112, v113
	v_max_f32_e32 v113, v113, v113
	v_max_f32_e32 v112, v112, v112
	v_max_f32_e32 v113, v112, v113
	v_cmp_ge_f32_e32 vcc, s49, v113
	s_cmp_eq_u64 vcc, exec
	v_mfma_f32_32x32x16_bf16 v[16:31], v[124:127], v[226:229], v[16:31]
	v_mov_b32_e32 v112, 1.0
	s_cbranch_scc0 .LBB0_230
